# ml_pass2 block loop: K/V loads for block j+2 issued a full iteration ahead (after block j+1 is copied to LDS)
# speedup vs baseline: 1.0120x; 1.0002x over previous
.LBB0_231:
	s_cmp_lt_i32 s19, s18
	s_cselect_b64 s[10:11], -1, 0
	s_cmp_ge_i32 s19, s18
	s_cbranch_scc1 .LBB0_233
	s_cmp_lg_u32 s19, 0
	s_cbranch_scc1 .LBB0_233
	s_waitcnt vmcnt(5)
	v_add_u32_e32 v0, s8, v98
	v_ashrrev_i32_e32 v1, 31, v0
	v_lshlrev_b64 v[2:3], 11, v[0:1]
	v_add_u32_e32 v0, 32, v0
	v_ashrrev_i32_e32 v1, 31, v0
	s_ashr_i32 s9, s8, 31
	v_lshlrev_b64 v[0:1], 11, v[0:1]
	s_lshl_b64 s[12:13], s[8:9], 1
	v_lshl_add_u64 v[2:3], v[86:87], 0, v[2:3]
	s_waitcnt vmcnt(4)
	v_lshl_add_u64 v[4:5], v[86:87], 0, v[0:1]
	s_waitcnt vmcnt(3)
	v_lshl_add_u64 v[8:9], v[88:89], 0, s[12:13]
	s_waitcnt vmcnt(2)
	v_lshl_add_u64 v[12:13], v[90:91], 0, s[12:13]
	s_waitcnt vmcnt(1)
	v_lshl_add_u64 v[16:17], v[92:93], 0, s[12:13]
	s_waitcnt vmcnt(0)
	v_lshl_add_u64 v[20:21], v[84:85], 0, s[12:13]
	global_load_dwordx4 v[0:3], v[2:3], off
	s_nop 0
	global_load_dwordx4 v[4:7], v[4:5], off
	s_nop 0
	global_load_dwordx4 v[8:11], v[8:9], off
	s_nop 0
	global_load_dwordx4 v[12:15], v[12:13], off
	s_nop 0
	global_load_dwordx4 v[16:19], v[16:17], off
	s_nop 0
	global_load_dwordx4 v[20:23], v[20:21], off
.LBB0_233:
	s_and_b32 s21, s19, 1
	s_mul_i32 s9, s21, 0xd400
	v_add_u32_e32 v120, s9, v107
	v_add_u32_e32 v121, v120, v111
	ds_read_b128 v[168:171], v121 offset:17408
	ds_read_b128 v[172:175], v121 offset:17472
	ds_read_b128 v[176:179], v121 offset:21760
	ds_read_b128 v[238:241], v121 offset:21824
	ds_read_b128 v[242:245], v121 offset:17536
	ds_read_b128 v[246:249], v121 offset:21888
	ds_read_b128 v[72:75], v121 offset:17600
	ds_read_b128 v[122:125], v121 offset:21952
	ds_read_b32 v130, v119
	ds_read_b32 v131, v119 offset:64
	s_waitcnt lgkmcnt(9)
	v_mfma_f32_16x16x32_bf16 v[76:79], v[56:59], v[168:171], 0
	s_waitcnt lgkmcnt(7)
	v_mfma_f32_16x16x32_bf16 v[126:129], v[56:59], v[176:179], 0
	s_waitcnt lgkmcnt(7)
	v_mfma_f32_16x16x32_bf16 v[76:79], v[60:63], v[172:175], v[76:79]
	s_waitcnt lgkmcnt(6)
	v_mfma_f32_16x16x32_bf16 v[126:129], v[60:63], v[238:241], v[126:129]
	s_waitcnt lgkmcnt(5)
	v_mfma_f32_16x16x32_bf16 v[76:79], v[64:67], v[242:245], v[76:79]
	s_waitcnt lgkmcnt(4)
	v_mfma_f32_16x16x32_bf16 v[126:129], v[64:67], v[246:249], v[126:129]
	s_waitcnt lgkmcnt(3)
	v_mfma_f32_16x16x32_bf16 v[76:79], v[68:71], v[72:75], v[76:79]
	s_waitcnt lgkmcnt(2)
	v_mfma_f32_16x16x32_bf16 v[126:129], v[68:71], v[122:125], v[126:129]
	s_waitcnt lgkmcnt(0)
	v_sub_f32_e32 v132, v130, v145
	v_sub_f32_e32 v133, v130, v146
	v_sub_f32_e32 v134, v130, v147
	v_sub_f32_e32 v135, v130, v158
	v_sub_f32_e32 v72, v131, v145
	v_sub_f32_e32 v73, v131, v146
	v_sub_f32_e32 v74, v131, v147
	v_sub_f32_e32 v75, v131, v158
	v_min_f32_e32 v132, 0, v132
	v_min_f32_e32 v133, 0, v133
	v_min_f32_e32 v134, 0, v134
	v_min_f32_e32 v135, 0, v135
	v_min_f32_e32 v72, 0, v72
	v_min_f32_e32 v73, 0, v73
	v_min_f32_e32 v74, 0, v74
	v_min_f32_e32 v75, 0, v75
	v_mul_f32_e32 v132, 0x3fb8aa3b, v132
	v_mul_f32_e32 v133, 0x3fb8aa3b, v133
	v_mul_f32_e32 v134, 0x3fb8aa3b, v134
	v_mul_f32_e32 v135, 0x3fb8aa3b, v135
	v_mul_f32_e32 v72, 0x3fb8aa3b, v72
	v_mul_f32_e32 v73, 0x3fb8aa3b, v73
	v_mul_f32_e32 v74, 0x3fb8aa3b, v74
	v_mul_f32_e32 v75, 0x3fb8aa3b, v75
	v_exp_f32_e32 v132, v132
	v_exp_f32_e32 v133, v133
	v_exp_f32_e32 v134, v134
	v_exp_f32_e32 v135, v135
	v_exp_f32_e32 v72, v72
	v_exp_f32_e32 v73, v73
	v_exp_f32_e32 v74, v74
	v_exp_f32_e32 v75, v75
	v_mul_f32_e32 v132, v76, v132
	v_mul_f32_e32 v133, v77, v133
	v_mul_f32_e32 v134, v78, v134
	v_mul_f32_e32 v135, v79, v135
	v_mul_f32_e32 v72, v126, v72
	v_mul_f32_e32 v73, v127, v73
	v_mul_f32_e32 v74, v128, v74
	v_mul_f32_e32 v75, v129, v75
	s_or_b64 s[22:23], s[0:1], s[10:11]
	v_cndmask_b32_e64 v132, 0, v132, s[22:23]
	s_or_b64 s[12:13], s[38:39], s[10:11]
	v_cndmask_b32_e64 v133, 0, v133, s[12:13]
	s_or_b64 s[22:23], s[40:41], s[10:11]
	v_cndmask_b32_e64 v134, 0, v134, s[22:23]
	s_or_b64 s[12:13], s[42:43], s[10:11]
	v_cndmask_b32_e64 v135, 0, v135, s[12:13]
	s_or_b64 s[22:23], s[44:45], s[10:11]
	v_cndmask_b32_e64 v72, 0, v72, s[22:23]
	s_or_b64 s[12:13], s[46:47], s[10:11]
	v_cndmask_b32_e64 v73, 0, v73, s[12:13]
	s_or_b64 s[22:23], s[48:49], s[10:11]
	v_cndmask_b32_e64 v74, 0, v74, s[22:23]
	s_or_b64 s[12:13], s[50:51], s[10:11]
	v_cndmask_b32_e64 v75, 0, v75, s[12:13]
	s_mul_i32 s9, s21, 0x2400
	s_add_i32 s9, s9, 16
	s_add_i32 s9, s9, 0x1ec00
	v_lshl_add_u32 v76, v110, 1, s9
	v_add_u32_e32 v76, v76, v113
	v_cvt_pk_bf16_f32 v132, v132, v132
	v_cvt_pk_bf16_f32 v133, v133, v133
	v_cvt_pk_bf16_f32 v134, v134, v134
	v_cvt_pk_bf16_f32 v135, v135, v135
	v_cvt_pk_bf16_f32 v72, v72, v72
	v_cvt_pk_bf16_f32 v73, v73, v73
	v_cvt_pk_bf16_f32 v74, v74, v74
	v_cvt_pk_bf16_f32 v75, v75, v75
	ds_write_b16 v76, v132
	ds_write_b16 v76, v133 offset:144
	ds_write_b16 v76, v134 offset:288
	ds_write_b16 v76, v135 offset:432
	ds_write_b16 v76, v72 offset:32
	ds_write_b16 v76, v73 offset:176
	ds_write_b16 v76, v74 offset:320
	ds_write_b16 v76, v75 offset:464
	s_andn2_b64 vcc, exec, s[10:11]
	s_waitcnt lgkmcnt(0)
	s_barrier
	s_cbranch_vccnz .LBB0_251
	s_xor_b32 s10, s21, 1
	s_mul_i32 s10, s10, 0xd400
	s_add_i32 s10, s10, 16
	v_add3_u32 v72, s10, v105, v156
	s_waitcnt vmcnt(5)
	ds_write_b128 v72, v[0:3] offset:17408
	s_waitcnt vmcnt(4)
	ds_write_b128 v72, v[4:7] offset:26112
	v_add3_u32 v72, s10, v106, v82
	s_waitcnt vmcnt(3)
	ds_write_b128 v72, v[8:11] offset:34816
	s_waitcnt vmcnt(2)
	ds_write_b128 v72, v[12:15] offset:44032
	s_waitcnt vmcnt(1)
	ds_write_b128 v72, v[16:19] offset:53248
	s_waitcnt vmcnt(0)
	ds_write_b128 v72, v[20:23] offset:62464
	s_add_i32 s2, s19, 1
	s_cmp_ge_i32 s2, s18
	s_cbranch_scc1 .Lml_pf_done
	s_add_i32 s2, s8, 64
	v_add_u32_e32 v0, s2, v98
	v_ashrrev_i32_e32 v1, 31, v0
	v_lshlrev_b64 v[2:3], 11, v[0:1]
	v_add_u32_e32 v0, 32, v0
	v_ashrrev_i32_e32 v1, 31, v0
	s_ashr_i32 s3, s2, 31
	v_lshlrev_b64 v[0:1], 11, v[0:1]
	s_lshl_b64 s[2:3], s[2:3], 1
	v_lshl_add_u64 v[2:3], v[86:87], 0, v[2:3]
	v_lshl_add_u64 v[4:5], v[86:87], 0, v[0:1]
	v_lshl_add_u64 v[8:9], v[88:89], 0, s[2:3]
	v_lshl_add_u64 v[12:13], v[90:91], 0, s[2:3]
	v_lshl_add_u64 v[16:17], v[92:93], 0, s[2:3]
	v_lshl_add_u64 v[20:21], v[84:85], 0, s[2:3]
	global_load_dwordx4 v[0:3], v[2:3], off
	s_nop 0
	global_load_dwordx4 v[4:7], v[4:5], off
	s_nop 0
	global_load_dwordx4 v[8:11], v[8:9], off
	s_nop 0
	global_load_dwordx4 v[12:15], v[12:13], off
	s_nop 0
	global_load_dwordx4 v[16:19], v[16:17], off
	s_nop 0
	global_load_dwordx4 v[20:23], v[20:21], off
.Lml_pf_done:
.LBB0_251:
	v_add3_u32 v134, s9, v108, v117
	v_add_u32_e32 v135, v120, v118
	ds_read_b128 v[72:75], v134
	ds_read_b128 v[76:79], v134 offset:2304
	ds_read_b128 v[122:125], v134 offset:4608
	ds_read_b128 v[126:129], v134 offset:6912
	ds_read_b128 v[130:133], v135 offset:34816
	s_waitcnt lgkmcnt(0)
	v_mfma_f32_16x16x32_bf16 v[24:27], v[72:75], v[130:133], v[24:27]
	v_mfma_f32_16x16x32_bf16 v[36:39], v[76:79], v[130:133], v[36:39]
	v_mfma_f32_16x16x32_bf16 v[32:35], v[122:125], v[130:133], v[32:35]
	v_mfma_f32_16x16x32_bf16 v[44:47], v[126:129], v[130:133], v[44:47]
	s_cmp_eq_u64 s[52:53], 0
	s_cbranch_scc1 .Lml_nd0
	v_mfma_f32_16x16x32_bf16 v[136:139], v[72:75], v[220:223], v[136:139]
	v_mfma_f32_16x16x32_bf16 v[140:143], v[76:79], v[220:223], v[140:143]
	v_mfma_f32_16x16x32_bf16 v[148:151], v[122:125], v[220:223], v[148:151]
	v_mfma_f32_16x16x32_bf16 v[152:155], v[126:129], v[220:223], v[152:155]
